# gdn_finalize row loop: all eight loads of an iteration issued together with counted waits (was four exposed round trips per iteration)
# baseline (speedup 1.0000x reference)
.LBB0_918:
	v_ashrrev_i32_e32 v10, 2, v14
	v_mov_b64_e32 v[18:19], s[38:39]
	v_mad_i64_i32 v[20:21], s[2:3], v10, s10, v[18:19]
	v_lshl_add_u64 v[20:21], v[20:21], 0, v[128:129]
	v_mov_b32_e32 v9, v129
	v_lshl_add_u64 v[20:21], v[20:21], 0, v[8:9]
	v_add_co_u32_e32 v20, vcc, s11, v20
	v_add_u32_e32 v12, v15, v14
	s_nop 0
	v_addc_co_u32_e32 v21, vcc, 0, v21, vcc
	global_load_dwordx2 v[54:55], v[20:21], off offset:1536
	v_ashrrev_i32_e32 v13, 31, v12
	v_add_u32_e32 v22, 4, v12
	v_lshlrev_b64 v[16:17], 8, v[12:13]
	v_ashrrev_i32_e32 v13, 2, v22
	v_mad_i64_i32 v[24:25], s[2:3], v13, s10, v[18:19]
	v_add_u32_e32 v26, 8, v12
	v_lshl_add_u64 v[24:25], v[24:25], 0, v[128:129]
	v_ashrrev_i32_e32 v13, 2, v26
	v_lshl_add_u64 v[24:25], v[24:25], 0, v[8:9]
	v_mad_i64_i32 v[28:29], s[2:3], v13, s10, v[18:19]
	v_add_u32_e32 v12, 12, v12
	v_add_co_u32_e32 v24, vcc, s11, v24
	v_lshl_add_u64 v[28:29], v[28:29], 0, v[128:129]
	v_ashrrev_i32_e32 v30, 2, v12
	v_addc_co_u32_e32 v25, vcc, 0, v25, vcc
	global_load_dwordx2 v[56:57], v[24:25], off offset:1536
	v_lshl_add_u64 v[28:29], v[28:29], 0, v[8:9]
	v_mad_i64_i32 v[18:19], s[2:3], v30, s10, v[18:19]
	v_add_co_u32_e32 v28, vcc, s11, v28
	v_lshl_add_u64 v[18:19], v[18:19], 0, v[128:129]
	s_nop 0
	v_addc_co_u32_e32 v29, vcc, 0, v29, vcc
	global_load_dwordx2 v[64:65], v[28:29], off offset:1536
	v_lshl_add_u64 v[18:19], v[18:19], 0, v[8:9]
	v_add_co_u32_e32 v18, vcc, s11, v18
	v_lshl_add_u64 v[16:17], v[4:5], 0, v[16:17]
	global_load_dwordx4 v[60:63], v[16:17], off
	s_nop 0
	v_addc_co_u32_e32 v19, vcc, 0, v19, vcc
	global_load_dwordx2 v[58:59], v[18:19], off offset:1536
	v_ashrrev_i32_e32 v23, 31, v22
	v_ashrrev_i32_e32 v11, 31, v10
	v_lshlrev_b64 v[22:23], 8, v[22:23]
	v_lshl_add_u64 v[22:23], v[4:5], 0, v[22:23]
	global_load_dwordx4 v[66:69], v[22:23], off
	s_mov_b32 s2, 0x358637bd
	v_or_b32_e32 v42, 1, v10
	v_ashrrev_i32_e32 v43, 31, v42
	v_ashrrev_i32_e32 v27, 31, v26
	v_ashrrev_i32_e32 v13, 31, v12
	v_lshlrev_b64 v[26:27], 8, v[26:27]
	v_lshlrev_b64 v[12:13], 8, v[12:13]
	v_lshl_add_u64 v[26:27], v[4:5], 0, v[26:27]
	global_load_dwordx4 v[70:73], v[26:27], off
	v_lshl_add_u64 v[12:13], v[4:5], 0, v[12:13]
	global_load_dwordx4 v[74:77], v[12:13], off
	v_add_u32_e32 v14, s25, v14
	s_waitcnt vmcnt(7)
	v_lshlrev_b32_e32 v32, 16, v54
	v_mul_f32_e32 v9, 0xbfb8aa3b, v32
	v_exp_f32_e32 v9, v9
	v_and_b32_e32 v33, 0xffff0000, v54
	v_lshlrev_b32_e32 v20, 16, v55
	v_and_b32_e32 v21, 0xffff0000, v55
	v_add_f32_e32 v9, 1.0, v9
	v_rcp_f32_e32 v38, v9
	v_mul_f32_e32 v9, 0xbfb8aa3b, v33
	v_exp_f32_e32 v9, v9
	s_waitcnt vmcnt(6)
	v_lshlrev_b32_e32 v44, 16, v56
	v_add_f32_e32 v9, 1.0, v9
	v_rcp_f32_e32 v39, v9
	v_mul_f32_e32 v9, 0xbfb8aa3b, v20
	v_exp_f32_e32 v9, v9
	v_and_b32_e32 v45, 0xffff0000, v56
	v_pk_mul_f32 v[32:33], v[38:39], v[32:33]
	s_waitcnt vmcnt(4)
	v_pk_mul_f32 v[36:37], v[60:61], v[60:61]
	v_add_f32_e32 v9, 1.0, v9
	v_rcp_f32_e32 v38, v9
	v_mul_f32_e32 v9, 0xbfb8aa3b, v21
	v_exp_f32_e32 v9, v9
	v_pk_mul_f32 v[34:35], v[62:63], v[62:63]
	v_lshlrev_b32_e32 v24, 16, v57
	v_and_b32_e32 v25, 0xffff0000, v57
	v_add_f32_e32 v9, 1.0, v9
	v_rcp_f32_e32 v39, v9
	v_mul_f32_e32 v9, 0xbfb8aa3b, v44
	v_exp_f32_e32 v9, v9
	v_pk_mul_f32 v[38:39], v[38:39], v[20:21]
	v_lshlrev_b64 v[20:21], 11, v[10:11]
	v_lshl_add_u64 v[40:41], v[6:7], 0, v[20:21]
	v_add_f32_e32 v9, 1.0, v9
	v_rcp_f32_e32 v50, v9
	v_mul_f32_e32 v9, 0xbfb8aa3b, v45
	v_exp_f32_e32 v9, v9
	s_waitcnt vmcnt(2)
	v_pk_mul_f32 v[48:49], v[66:67], v[66:67]
	v_add_f32_e32 v9, 1.0, v9
	v_rcp_f32_e32 v51, v9
	v_pk_mul_f32 v[46:47], v[68:69], v[68:69]
	v_pk_mul_f32 v[44:45], v[50:51], v[44:45]
	v_mov_b32_e32 v50, v48
	v_mov_b32_e32 v51, v36
	v_mov_b32_e32 v36, v49
	v_pk_add_f32 v[36:37], v[50:51], v[36:37]
	v_mov_b32_e32 v48, v46
	v_mov_b32_e32 v49, v34
	v_pk_add_f32 v[36:37], v[36:37], v[48:49]
	v_mov_b32_e32 v34, v47
	v_pk_add_f32 v[34:35], v[36:37], v[34:35]
	s_nop 1
	v_mov_b32_dpp v37, v35 row_ror:8 row_mask:0xf bank_mask:0xf bound_ctrl:1
	v_mov_b32_dpp v36, v34 row_ror:8 row_mask:0xf bank_mask:0xf bound_ctrl:1
	v_pk_add_f32 v[34:35], v[34:35], v[36:37]
	s_nop 1
	v_mov_b32_dpp v37, v35 row_ror:4 row_mask:0xf bank_mask:0xf bound_ctrl:1
	v_mov_b32_dpp v36, v34 row_ror:4 row_mask:0xf bank_mask:0xf bound_ctrl:1
	v_pk_add_f32 v[34:35], v[34:35], v[36:37]
	s_nop 1
	v_mov_b32_dpp v37, v35 quad_perm:[2,3,0,1] row_mask:0xf bank_mask:0xf bound_ctrl:1
	v_mov_b32_dpp v36, v34 quad_perm:[2,3,0,1] row_mask:0xf bank_mask:0xf bound_ctrl:1
	v_pk_add_f32 v[34:35], v[34:35], v[36:37]
	s_nop 1
	v_mov_b32_dpp v37, v35 quad_perm:[1,0,3,2] row_mask:0xf bank_mask:0xf bound_ctrl:1
	v_mov_b32_dpp v36, v34 quad_perm:[1,0,3,2] row_mask:0xf bank_mask:0xf bound_ctrl:1
	v_pk_add_f32 v[34:35], v[34:35], v[36:37]
	v_mov_b64_e32 v[36:37], s[2:3]
	v_pk_fma_f32 v[34:35], v[34:35], s[44:45], v[36:37] op_sel_hi:[1,0,0]
	s_mov_b32 s2, 0x1ffff
	v_mul_f32_e32 v9, 0x4b800000, v35
	v_cmp_gt_f32_e64 s[42:43], s28, v35
	v_cmp_gt_f32_e32 vcc, s28, v34
	s_nop 0
	v_cndmask_b32_e64 v9, v35, v9, s[42:43]
	v_rsq_f32_e32 v9, v9
	v_and_b32_e32 v35, 0xffff0000, v64
	v_mul_f32_e32 v11, 0x45800000, v9
	v_cndmask_b32_e64 v46, v9, v11, s[42:43]
	v_mul_f32_e32 v9, 0x4b800000, v34
	v_cndmask_b32_e32 v9, v34, v9, vcc
	v_rsq_f32_e32 v9, v9
	v_pk_mul_f32 v[16:17], v[60:61], v[46:47] op_sel_hi:[1,0]
	v_pk_mul_f32 v[18:19], v[62:63], v[46:47] op_sel_hi:[1,0]
	v_pk_mul_f32 v[16:17], v[0:1], v[16:17]
	v_mul_f32_e32 v11, 0x45800000, v9
	v_pk_mul_f32 v[16:17], v[32:33], v[16:17]
	v_pk_mul_f32 v[18:19], v[2:3], v[18:19]
	v_cvt_pk_bf16_f32 v32, v16, v17
	v_cndmask_b32_e32 v16, v9, v11, vcc
	v_mul_f32_e32 v9, 0xbfb8aa3b, v24
	v_exp_f32_e32 v9, v9
	v_pk_mul_f32 v[18:19], v[38:39], v[18:19]
	v_lshlrev_b32_e32 v34, 16, v64
	v_cvt_pk_bf16_f32 v33, v18, v19
	v_add_f32_e32 v9, 1.0, v9
	v_pk_mul_f32 v[18:19], v[66:67], v[16:17] op_sel_hi:[1,0]
	v_rcp_f32_e32 v20, v9
	v_mul_f32_e32 v9, 0xbfb8aa3b, v25
	v_exp_f32_e32 v9, v9
	v_pk_mul_f32 v[16:17], v[68:69], v[16:17] op_sel_hi:[1,0]
	v_lshlrev_b32_e32 v28, 16, v65
	v_pk_mul_f32 v[16:17], v[2:3], v[16:17]
	v_add_f32_e32 v9, 1.0, v9
	v_rcp_f32_e32 v21, v9
	v_mul_f32_e32 v9, 0xbfb8aa3b, v34
	v_exp_f32_e32 v9, v9
	v_and_b32_e32 v29, 0xffff0000, v65
	v_pk_mul_f32 v[20:21], v[20:21], v[24:25]
	v_pk_mul_f32 v[18:19], v[0:1], v[18:19]
	v_pk_mul_f32 v[16:17], v[20:21], v[16:17]
	v_add_f32_e32 v9, 1.0, v9
	v_cvt_pk_bf16_f32 v21, v16, v17
	v_lshlrev_b64 v[16:17], 11, v[42:43]
	v_rcp_f32_e32 v42, v9
	v_mul_f32_e32 v9, 0xbfb8aa3b, v35
	v_exp_f32_e32 v9, v9
	v_pk_mul_f32 v[18:19], v[44:45], v[18:19]
	v_lshl_add_u64 v[22:23], v[6:7], 0, v[16:17]
	v_cvt_pk_bf16_f32 v20, v18, v19
	v_add_f32_e32 v9, 1.0, v9
	v_rcp_f32_e32 v43, v9
	v_mul_f32_e32 v9, 0xbfb8aa3b, v28
	v_exp_f32_e32 v9, v9
	v_or_b32_e32 v24, 2, v10
	v_pk_mul_f32 v[34:35], v[42:43], v[34:35]
	v_add_f32_e32 v9, 1.0, v9
	v_rcp_f32_e32 v42, v9
	v_mul_f32_e32 v9, 0xbfb8aa3b, v29
	v_exp_f32_e32 v9, v9
	v_lshlrev_b32_e32 v44, 16, v58
	v_and_b32_e32 v45, 0xffff0000, v58
	v_ashrrev_i32_e32 v25, 31, v24
	v_add_f32_e32 v9, 1.0, v9
	v_rcp_f32_e32 v43, v9
	v_mul_f32_e32 v9, 0xbfb8aa3b, v44
	v_exp_f32_e32 v9, v9
	v_lshlrev_b64 v[24:25], 11, v[24:25]
	v_pk_mul_f32 v[28:29], v[42:43], v[28:29]
	v_or_b32_e32 v42, 3, v10
	s_nop 0
	global_store_dwordx2 v[40:41], v[32:33], off
	global_store_dwordx2 v[22:23], v[20:21], off
	v_add_f32_e32 v9, 1.0, v9
	v_rcp_f32_e32 v50, v9
	v_mul_f32_e32 v9, 0xbfb8aa3b, v45
	v_exp_f32_e32 v9, v9
	v_lshl_add_u64 v[24:25], v[6:7], 0, v[24:25]
	v_lshlrev_b32_e32 v30, 16, v59
	v_and_b32_e32 v31, 0xffff0000, v59
	v_add_f32_e32 v9, 1.0, v9
	v_rcp_f32_e32 v51, v9
	v_ashrrev_i32_e32 v43, 31, v42
	v_pk_mul_f32 v[44:45], v[50:51], v[44:45]
	s_waitcnt vmcnt(3)
	v_pk_mul_f32 v[38:39], v[70:71], v[70:71]
	v_pk_mul_f32 v[26:27], v[72:73], v[72:73]
	v_mov_b32_e32 v21, v38
	v_mov_b32_e32 v23, v26
	s_waitcnt vmcnt(2)
	v_pk_mul_f32 v[48:49], v[74:75], v[74:75]
	v_pk_mul_f32 v[46:47], v[76:77], v[76:77]
	v_mov_b32_e32 v20, v48
	v_mov_b32_e32 v38, v49
	v_pk_add_f32 v[20:21], v[20:21], v[38:39]
	v_mov_b32_e32 v22, v46
	v_pk_add_f32 v[20:21], v[20:21], v[22:23]
	v_mov_b32_e32 v26, v47
	v_pk_add_f32 v[20:21], v[20:21], v[26:27]
	s_nop 1
	v_mov_b32_dpp v23, v21 row_ror:8 row_mask:0xf bank_mask:0xf bound_ctrl:1
	v_mov_b32_dpp v22, v20 row_ror:8 row_mask:0xf bank_mask:0xf bound_ctrl:1
	v_pk_add_f32 v[20:21], v[20:21], v[22:23]
	s_nop 1
	v_mov_b32_dpp v23, v21 row_ror:4 row_mask:0xf bank_mask:0xf bound_ctrl:1
	v_mov_b32_dpp v22, v20 row_ror:4 row_mask:0xf bank_mask:0xf bound_ctrl:1
	v_pk_add_f32 v[20:21], v[20:21], v[22:23]
	s_nop 1
	v_mov_b32_dpp v23, v21 quad_perm:[2,3,0,1] row_mask:0xf bank_mask:0xf bound_ctrl:1
	v_mov_b32_dpp v22, v20 quad_perm:[2,3,0,1] row_mask:0xf bank_mask:0xf bound_ctrl:1
	v_pk_add_f32 v[20:21], v[20:21], v[22:23]
	s_nop 1
	v_mov_b32_dpp v23, v21 quad_perm:[1,0,3,2] row_mask:0xf bank_mask:0xf bound_ctrl:1
	v_mov_b32_dpp v22, v20 quad_perm:[1,0,3,2] row_mask:0xf bank_mask:0xf bound_ctrl:1
	v_pk_add_f32 v[20:21], v[20:21], v[22:23]
	s_nop 0
	v_pk_fma_f32 v[20:21], v[20:21], s[44:45], v[36:37] op_sel_hi:[1,0,0]
	s_nop 0
	v_mul_f32_e32 v9, 0x4b800000, v21
	v_cmp_gt_f32_e64 s[42:43], s28, v21
	v_cmp_gt_f32_e32 vcc, s28, v20
	s_nop 0
	v_cndmask_b32_e64 v9, v21, v9, s[42:43]
	v_rsq_f32_e32 v9, v9
	s_nop 0
	v_mul_f32_e32 v21, 0x45800000, v9
	v_cndmask_b32_e64 v22, v9, v21, s[42:43]
	v_mul_f32_e32 v9, 0x4b800000, v20
	v_cndmask_b32_e32 v9, v20, v9, vcc
	v_pk_mul_f32 v[16:17], v[70:71], v[22:23] op_sel_hi:[1,0]
	v_pk_mul_f32 v[18:19], v[72:73], v[22:23] op_sel_hi:[1,0]
	v_rsq_f32_e32 v9, v9
	v_pk_mul_f32 v[16:17], v[0:1], v[16:17]
	v_pk_mul_f32 v[18:19], v[2:3], v[18:19]
	v_pk_mul_f32 v[16:17], v[34:35], v[16:17]
	v_pk_mul_f32 v[18:19], v[28:29], v[18:19]
	v_cvt_pk_bf16_f32 v16, v16, v17
	v_cvt_pk_bf16_f32 v17, v18, v19
	global_store_dwordx2 v[24:25], v[16:17], off
	v_mul_f32_e32 v16, 0x45800000, v9
	v_cndmask_b32_e32 v16, v9, v16, vcc
	v_mul_f32_e32 v9, 0xbfb8aa3b, v30
	v_exp_f32_e32 v9, v9
	v_pk_mul_f32 v[10:11], v[74:75], v[16:17] op_sel_hi:[1,0]
	v_pk_mul_f32 v[12:13], v[76:77], v[16:17] op_sel_hi:[1,0]
	v_pk_mul_f32 v[10:11], v[0:1], v[10:11]
	v_add_f32_e32 v9, 1.0, v9
	v_rcp_f32_e32 v18, v9
	v_mul_f32_e32 v9, 0xbfb8aa3b, v31
	v_exp_f32_e32 v9, v9
	v_pk_mul_f32 v[12:13], v[2:3], v[12:13]
	v_pk_mul_f32 v[10:11], v[44:45], v[10:11]
	v_cmp_lt_i32_e32 vcc, s2, v14
	v_add_f32_e32 v9, 1.0, v9
	v_rcp_f32_e32 v19, v9
	v_cvt_pk_bf16_f32 v10, v10, v11
	s_or_b64 s[40:41], vcc, s[40:41]
	v_pk_mul_f32 v[16:17], v[18:19], v[30:31]
	s_nop 0
	v_pk_mul_f32 v[12:13], v[16:17], v[12:13]
	s_nop 0
	v_cvt_pk_bf16_f32 v11, v12, v13
	v_lshlrev_b64 v[12:13], 11, v[42:43]
	v_lshl_add_u64 v[12:13], v[6:7], 0, v[12:13]
	global_store_dwordx2 v[12:13], v[10:11], off
	s_andn2_b64 exec, exec, s[40:41]
	s_cbranch_execnz .LBB0_918
